# conv phase: XCD-contiguous block order (halo rows shared in one L2) + NA bias sentinel column
# speedup vs baseline: 1.0035x; 1.0003x over previous
.LBB0_1802:
	s_mov_b64 s[20:21], 0
	s_mov_b64 s[2:3], 0
	s_mov_b32 s40, s68
	v_readlane_b32 s0, v254, 19
	s_cmpk_lg_i32 s0, 0x100
	s_cbranch_scc1 .Lcv_noremap
	s_and_b32 s0, s68, 7
	s_lshl_b32 s0, s0, 5
	s_lshr_b32 s40, s68, 3
	s_or_b32 s40, s40, s0
.Lcv_noremap:
	v_mov_b32_e32 v0, v181
	v_readlane_b32 s0, v254, 19
	s_lshl_b32 s34, s0, 9
	v_lshl_add_u32 v97, s40, 9, v0
	s_mov_b32 s0, 0xc0000
	v_readlane_b32 s1, v254, 20
	v_cmp_gt_i32_e32 vcc, s0, v97
	s_and_saveexec_b64 s[0:1], vcc
	s_cbranch_execz .LBB0_1813
	v_readlane_b32 s44, v254, 0
	v_readlane_b32 s56, v254, 12
	v_readlane_b32 s57, v254, 13
	s_add_u32 s22, s56, s20
	s_addc_u32 s23, s57, s21
	v_readlane_b32 s20, v254, 39
	v_readlane_b32 s21, v254, 40
	s_mov_b32 s26, s20
	s_mulk_i32 s20, 0xf00
	s_ashr_i32 s21, s20, 31
	s_lshl_b64 s[20:21], s[20:21], 2
	s_add_u32 s22, s22, s20
	v_readlane_b32 s58, v254, 14
	s_addc_u32 s23, s23, s21
	v_readlane_b32 s59, v254, 15
	s_add_u32 s20, s58, s2
	s_mul_i32 s2, s26, 0x300
	s_addc_u32 s21, s59, s3
	s_ashr_i32 s3, s2, 31
	s_lshl_b64 s[2:3], s[2:3], 2
	s_add_u32 s26, s20, s2
	s_addc_u32 s27, s21, s3
	v_readlane_b32 s2, v254, 25
	v_readlane_b32 s3, v254, 26
	s_add_u32 s2, s78, s2
	s_addc_u32 s3, s79, s3
	s_add_u32 s38, s2, 0x28600000
	s_addc_u32 s39, s3, 0
	v_lshlrev_b32_e32 v0, 3, v0
	v_readlane_b32 s2, v254, 19
	v_lshl_add_u32 v96, s40, 12, v0
	s_lshl_b32 s20, s2, 12
	s_mov_b64 s[40:41], 0
	v_readlane_b32 s45, v254, 1
	v_readlane_b32 s46, v254, 2
	v_readlane_b32 s47, v254, 3
	v_readlane_b32 s48, v254, 4
	v_readlane_b32 s49, v254, 5
	v_readlane_b32 s50, v254, 6
	v_readlane_b32 s51, v254, 7
	v_readlane_b32 s52, v254, 8
	v_readlane_b32 s53, v254, 9
	v_readlane_b32 s54, v254, 10
	v_readlane_b32 s55, v254, 11
	v_readlane_b32 s3, v254, 20
	s_branch .LBB0_1805
